# PA: rstd-table reduction moved behind the GEMM prologue's first DMA loads as in PE, private barrier removed
# baseline (speedup 1.0000x reference)
; #define RSTD_TABLE(arr, np_, ps_) { pg8::Unit u0; const bool any = S.next(0, u0); __syncthreads(); \
;         if (any && tid < 256) rtab[tid] = rsqrtf(pg8::row_ssq((arr), (np_), u0.pm * 256 + tid, (ps_)) * (1.0f / 1024.0f) + pg8::RMS_EPS); __syncthreads(); }
; __device__ __forceinline__ float row_ssq(const float* ssq, int np, int row, int pstride) {
;     if (np == 1) return ssq[row];
;     const f32x4* q = (const f32x4*)(ssq + (size_t)(row >> 8) * pstride + (row & 255) * 16);
;     const f32x4 a = q[0], b = q[1], c = q[2], d = q[3];
;     return (((a[0] + a[1]) + (a[2] + a[3])) + ((b[0] + b[1]) + (b[2] + b[3]))) + (((c[0] + c[1]) + (c[2] + c[3])) + ((d[0] + d[1]) + (d[2] + d[3])));
; __global__ void __launch_bounds__(NWAVES * 64, 2) mk_fwd(Args args) {
;     ...
;     for (int l = 0; l < DEPTH; ++l) {
;         const int pb = 1 + 6 * l;
;         unsigned char* wl = ws + WS_W + (size_t)l * W_LAYER;
;         for (int rep = 0; rep < ((DBG_DOUBLE & 2) ? 2 : 1); ++rep)
;         if (IN(pb + 0) && (DBG_MASK & 2)) {
;             pg8::Gemm g{HB, (const bf16*)(wl + WO_IN), DM, DM, DM}; pg8::StaticOrder S; S.init(M, INW, G, (int)blockIdx.x, 1);
;             RSTD_TABLE(SSQ_ARR(2 * l), SSQ_NP(2 * l), SSQ_PS(2 * l));
.LBB0_114:
	v_writelane_b32 v238, s12, 40
	s_xor_b64 s[6:7], s[12:13], -1
	s_mul_i32 s24, s16, 0x1b00000
	v_writelane_b32 v238, s13, 41
	v_writelane_b32 v238, s6, 42
	s_nop 1
	v_writelane_b32 v238, s7, 43
	s_mul_i32 s6, s16, 6
	v_writelane_b32 v238, s6, 44
	s_or_b32 s23, s6, 1
	s_mov_b32 s6, s16
	v_writelane_b32 v238, s6, 45
	s_nop 1
	v_writelane_b32 v238, s7, 46
	v_readlane_b32 s6, v242, 41
	v_readlane_b32 s7, v242, 42
	s_add_u32 s42, s6, s24
	s_addc_u32 s43, s7, 0
	s_cmp_le_i32 s4, s23
	s_cselect_b64 s[24:25], -1, 0
	s_cmp_lt_i32 s23, s5
	s_cselect_b64 s[26:27], -1, 0
	s_and_b64 s[40:41], s[24:25], s[26:27]
	s_add_u32 s6, s42, 0x1580000
	s_addc_u32 s7, s43, 0
	s_add_u32 s58, s42, 0xa80000
	s_addc_u32 s59, s43, 0
	s_add_u32 s92, s42, 0x880000
	v_writelane_b32 v238, s6, 47
	s_addc_u32 s93, s43, 0
	s_add_u32 s56, s42, 0x680000
	v_writelane_b32 v238, s7, 48
	s_addc_u32 s57, s43, 0
	s_andn2_b64 vcc, exec, s[40:41]
	v_writelane_b32 v238, s50, 49
	s_nop 1
	v_writelane_b32 v238, s51, 50
	s_cbranch_vccnz .LBB0_168
	v_readlane_b32 s6, v242, 54
	v_readlane_b32 s7, v242, 55
	s_and_b64 s[24:25], s[6:7], exec
	v_readlane_b32 s6, v241, 41
	v_readlane_b32 s7, v241, 42
	v_readlane_b32 s12, v238, 27
	v_readlane_b32 s13, v238, 28
	s_cselect_b32 s12, s6, s12
	v_readlane_b32 s6, v242, 56
	v_writelane_b32 v238, s12, 27
	v_readlane_b32 s7, v242, 57
	s_waitcnt lgkmcnt(0)
	v_writelane_b32 v238, s13, 28
	s_barrier
	s_and_saveexec_b64 s[36:37], s[6:7]
	v_readlane_b32 s64, v242, 60
	v_readlane_b32 s16, v242, 62
	v_readlane_b32 s18, v240, 0
	v_readlane_b32 s60, v240, 2
	v_readlane_b32 s65, v242, 61
	v_readlane_b32 s17, v242, 63
	v_readlane_b32 s19, v240, 1
	v_readlane_b32 s61, v240, 3
	v_readlane_b32 s62, v239, 8
	s_cbranch_execz .LBB0_121
	v_readlane_b32 s6, v238, 42
	v_readlane_b32 s7, v238, 43
	s_mov_b64 s[38:39], -1
	s_and_b64 vcc, exec, s[6:7]
	s_cbranch_vccz .LBB0_118
	v_readlane_b32 s6, v238, 45
	v_readlane_b32 s7, v238, 46
	s_lshl_b32 s23, s6, 1
	s_add_i32 s84, s23, -1
	v_readlane_b32 s6, v238, 27
	s_lshl_b64 s[24:25], s[84:85], 14
	s_mov_b32 s12, s6
	s_ashr_i32 s13, s6, 31
	v_lshl_add_u64 v[204:205], v[160:161], 0, s[24:25]
	s_lshl_b64 s[24:25], s[12:13], 20
	v_lshl_add_u64 v[216:217], v[204:205], 0, s[24:25]
	global_load_dwordx4 v[204:207], v[216:217], off
	global_load_dwordx4 v[208:211], v[216:217], off offset:32
	global_load_dwordx4 v[212:215], v[216:217], off offset:16
	s_nop 0
	global_load_dwordx4 v[216:219], v[216:217], off offset:48
	s_mov_b64 s[38:39], 0
.LBB0_118:
	s_andn2_b64 vcc, exec, s[38:39]
	s_cbranch_vccnz .LBB0_120
	v_readlane_b32 s6, v238, 27
	v_readlane_b32 s7, v238, 28
	s_nop 0
	v_lshl_or_b32 v204, s6, 8, v0
	v_readlane_b32 s6, v242, 49
	v_ashrrev_i32_e32 v205, 31, v204
	v_readlane_b32 s7, v242, 50
	s_nop 1
	v_lshl_add_u64 v[204:205], v[204:205], 2, s[6:7]
	global_load_dword v204, v[204:205], off
; #define PG8_BAR __builtin_amdgcn_s_barrier()
; __device__ __forceinline__ float row_ssq(const float* ssq, int np, int row, int pstride) {
;     if (np == 1) return ssq[row];
;     const f32x4* q = (const f32x4*)(ssq + (size_t)(row >> 8) * pstride + (row & 255) * 16);
;     const f32x4 a = q[0], b = q[1], c = q[2], d = q[3];
; template <class Epi, class Sched, bool ALIGN_EPI = false, bool SP2 = false>
; __device__ __forceinline__ void gemm_phase(PG8_LAS unsigned char* lds, const Gemm g, const Sched& S, const Epi& E) {
;     int tid_o = threadIdx.x; asm volatile("" : "+v"(tid_o));
;     const int tid = tid_o, wid = __builtin_amdgcn_readfirstlane(tid >> 6), lane = tid & 63, wr = wid >> 2, wc = wid & 3, fr = lane & 15, fq = lane >> 4;
;     const int K = g.K, nt = K / BK, ld = g.ld, ldb = g.ldb;
;     unsigned voffA[2], voffB[2];
; #pragma unroll
;     for (int i = 0; i < 2; ++i) { int R, C; stage_rc(tid * 16 + i * 8192, R, C); const int Rb = Epi::PERM ? ((R & ~31) + perm32(R & 31)) : R;
;         voffA[i] = (unsigned)(R * ld + C) * 2u; voffB[i] = (unsigned)(Rb * ldb + C) * 2u; }
;     const unsigned kstep = (unsigned)(BK * 2);
;     const unsigned hstep = (unsigned)HALF * (unsigned)ld * 2u;
;     const unsigned tstep = 2u * hstep;
;     const unsigned hstepB = (unsigned)HALF * (unsigned)ldb * 2u, tstepB = 2u * hstepB;
;     const unsigned ldsw = (unsigned)wid * 1024u;
;     const int aoff = lds_byte(wr * 64 + fr, fq * 8), boff = lds_byte(wc * 32 + fr, fq * 8);
;     ...
;     Unit cur, nxt; int ui = 0;
;     if (!S.next(0, cur)) return;
;     f32x4 acc[2][2][4][2];
; #pragma unroll
;     for (int a = 0; a < 2; ++a)
; #pragma unroll
;         for (int b = 0; b < 2; ++b)
; #pragma unroll
;             for (int m = 0; m < 4; ++m)
; #pragma unroll
;                 for (int n = 0; n < 2; ++n) acc[a][b][m][n] = (f32x4){0.f, 0.f, 0.f, 0.f};
;     bf16x8 At[4][2], B0[2][2], B1[2][2];
;     const char* cA = (const char*)g.A + (size_t)cur.pm * tstep + (size_t)cur.seg * K * 2; const char* cB = (const char*)g.Bt + (size_t)cur.pn * tstepB + (size_t)cur.seg * K * 2;
;     if constexpr (SP2) {
;         PG8_STAGE(PG8_SB(0, 0), cB, voffB); PG8_STAGE(PG8_SB(0, 1), cB + hstepB, voffB); PG8_STAGE(PG8_SA(0, 0), cA, voffA); PG8_STAGE(PG8_SA(0, 1), cA + hstep, voffA);
;         if (wr == 1) PG8_BAR;
.LBB0_120:
.LBB0_121:
	s_or_b64 exec, exec, s[36:37]
	v_readlane_b32 s6, v242, 54
	v_mov_b32_e32 v8, v0
	v_readlane_b32 s7, v242, 55
	s_andn2_b64 vcc, exec, s[6:7]
	v_readfirstlane_b32 s31, v8
	s_cbranch_vccnz .LBB0_170
	v_lshlrev_b32_e32 v2, 4, v8
	v_add_u32_e32 v3, 0x2000, v2
	v_ashrrev_i32_e32 v4, 31, v3
	v_lshrrev_b32_e32 v4, 22, v4
	v_add_u32_e32 v4, v3, v4
	v_ashrrev_i32_e32 v6, 10, v4
	v_mul_i32_i24_e32 v4, 0x400, v6
	v_sub_u32_e32 v3, v3, v4
	v_lshrrev_b32_e32 v4, 4, v3
	v_bitop3_b32 v3, v4, v3, 32 bitop3:0x6c
	v_ashrrev_i32_e32 v4, 31, v3
	v_lshrrev_b32_e32 v4, 26, v4
	v_add_u32_e32 v4, v3, v4
	v_lshlrev_b32_e32 v5, 3, v6
	v_ashrrev_i32_e32 v7, 6, v4
	v_and_b32_e32 v5, -16, v5
	v_add_u32_e32 v5, v7, v5
	v_and_b32_e32 v9, 3, v7
	s_mov_b32 s6, 0x1fffe0
	v_lshrrev_b32_e32 v10, 2, v5
	v_lshlrev_b32_e32 v11, 1, v5
	v_and_b32_e32 v4, 0xc0, v4
	v_and_or_b32 v9, v5, s6, v9
	v_and_b32_e32 v10, 4, v10
	v_and_b32_e32 v11, 24, v11
	v_sub_u32_e32 v3, v3, v4
	v_or3_b32 v10, v9, v10, v11
	v_lshlrev_b32_e32 v9, 5, v6
	v_ashrrev_i16_sdwa v3, v196, sext(v3) dst_sel:DWORD dst_unused:UNUSED_PAD src0_sel:DWORD src1_sel:BYTE_0
	v_and_b32_e32 v11, 32, v9
	v_bfe_i32 v9, v3, 0, 16
	v_add_lshl_u32 v3, v11, v9, 1
	v_lshl_add_u32 v132, v10, 11, v3
	v_lshl_add_u32 v134, v5, 11, v3
	v_bfe_i32 v3, v8, 27, 1
	v_lshrrev_b32_e32 v3, 22, v3
	v_add_u32_e32 v3, v2, v3
	v_and_b32_e32 v3, 0xfffffc00, v3
	v_sub_u32_e32 v2, v2, v3
	v_lshrrev_b32_e32 v3, 4, v2
	v_ashrrev_i32_e32 v4, 31, v8
	v_bitop3_b32 v2, v3, v2, 32 bitop3:0x6c
	v_lshrrev_b32_e32 v4, 26, v4
	v_ashrrev_i32_e32 v3, 31, v2
	v_add_u32_e32 v4, v8, v4
	v_lshrrev_b32_e32 v3, 26, v3
	v_ashrrev_i32_e32 v11, 6, v4
	v_add_u32_e32 v3, v2, v3
	v_lshlrev_b32_e32 v4, 3, v11
	v_ashrrev_i32_e32 v10, 6, v3
	v_and_b32_e32 v4, -16, v4
	v_add_u32_e32 v4, v10, v4
	v_and_b32_e32 v5, 3, v10
	v_lshrrev_b32_e32 v12, 2, v4
	v_lshlrev_b32_e32 v13, 1, v4
	v_and_b32_e32 v3, 0xc0, v3
	s_ashr_i32 s28, s31, 6
	v_and_or_b32 v5, v4, s6, v5
	v_and_b32_e32 v12, 4, v12
	v_and_b32_e32 v13, 24, v13
	v_sub_u32_e32 v2, v2, v3
	s_ashr_i32 s30, s31, 8
	s_lshl_b32 s23, s28, 10
	v_or3_b32 v5, v5, v12, v13
	v_lshlrev_b32_e32 v12, 5, v11
	v_ashrrev_i16_sdwa v2, v196, sext(v2) dst_sel:DWORD dst_unused:UNUSED_PAD src0_sel:DWORD src1_sel:BYTE_0
	v_readlane_b32 s6, v241, 39
	v_and_b32_e32 v13, 32, v12
	v_bfe_i32 v12, v2, 0, 16
	v_readlane_b32 s7, v241, 40
	s_add_u32 s38, s42, s6
	v_add_lshl_u32 v2, v13, v12, 1
	s_addc_u32 s39, s43, s7
	s_add_i32 s24, s23, 0
	v_lshl_add_u32 v136, v5, 11, v2
	s_add_i32 m0, s24, 0x10000
	v_readlane_b32 s6, v241, 43
	global_load_lds_dwordx4 v136, s[38:39]
	s_add_i32 m0, s24, 0x12000
	s_add_u32 s26, s38, 0x40000
	global_load_lds_dwordx4 v132, s[38:39]
	s_addc_u32 s27, s39, 0
	s_add_i32 m0, s24, 0x14000
	v_lshl_add_u32 v138, v4, 11, v2
	global_load_lds_dwordx4 v136, s[26:27]
	s_add_i32 m0, s24, 0x16000
	v_readlane_b32 s7, v241, 44
	global_load_lds_dwordx4 v132, s[26:27]
	s_mov_b32 m0, s24
	s_add_i32 s25, s24, 0x2000
	s_add_i32 s26, s24, 0x4000
	s_nop 0
	global_load_lds_dwordx4 v138, s[6:7]
	s_mov_b32 m0, s25
	s_add_i32 s27, s24, 0x6000
	global_load_lds_dwordx4 v134, s[6:7]
	v_readlane_b32 s6, v241, 45
	s_mov_b32 m0, s26
	v_readlane_b32 s7, v241, 46
	v_mov_b32_e32 v137, v66
	v_mov_b32_e32 v133, v66
	s_cmp_eq_u32 s30, 1
	v_lshl_add_u64 v[2:3], s[38:39], 0, v[136:137]
	s_cselect_b64 s[44:45], -1, 0
	global_load_lds_dwordx4 v138, s[6:7]
	s_mov_b32 m0, s27
	s_cmp_lg_u32 s30, 1
	global_load_lds_dwordx4 v134, s[6:7]
	v_lshl_add_u64 v[4:5], s[38:39], 0, v[132:133]
	s_waitcnt vmcnt(8)
	v_readlane_b32 s6, v242, 56
	v_readlane_b32 s7, v242, 57
	s_nop 1
	s_and_saveexec_b64 s[36:37], s[6:7]
	s_cbranch_execz .Lrs_pa_done
	v_readlane_b32 s6, v238, 42
	v_readlane_b32 s7, v238, 43
	s_nop 1
	s_and_b64 vcc, exec, s[6:7]
	s_cbranch_vccz .Lrs_pa_l0
	v_mov_b32_e32 v220, v204
	v_mov_b32_e32 v221, v208
	v_mov_b32_e32 v208, v205
	v_mov_b32_e32 v204, v206
	v_mov_b32_e32 v205, v210
	v_mov_b32_e32 v210, v207
	v_mov_b32_e32 v206, v212
	v_mov_b32_e32 v207, v216
	v_mov_b32_e32 v216, v213
	v_mov_b32_e32 v212, v214
	v_mov_b32_e32 v213, v218
	v_mov_b32_e32 v218, v215
	v_pk_add_f32 v[208:209], v[220:221], v[208:209]
	v_pk_add_f32 v[204:205], v[204:205], v[210:211]
	v_pk_add_f32 v[206:207], v[206:207], v[216:217]
	v_pk_add_f32 v[210:211], v[212:213], v[218:219]
	v_pk_add_f32 v[204:205], v[208:209], v[204:205]
	v_pk_add_f32 v[206:207], v[206:207], v[210:211]
	v_pk_add_f32 v[204:205], v[204:205], v[206:207]
	s_nop 0
	v_add_f32_e32 v204, v204, v205
.Lrs_pa_l0:
	v_fmamk_f32 v204, v204, 0x3a800000, v195
	s_mov_b32 s6, 0x800000
	v_mul_f32_e32 v205, 0x4b800000, v204
	v_cmp_gt_f32_e32 vcc, s6, v204
	s_nop 1
	v_cndmask_b32_e32 v204, v204, v205, vcc
	v_rsq_f32_e32 v204, v204
	s_nop 0
	v_mul_f32_e32 v205, 0x45800000, v204
	v_cndmask_b32_e32 v204, v204, v205, vcc
	ds_write_b32 v1, v204
.Lrs_pa_done:
	s_or_b64 exec, exec, s[36:37]
	s_cmp_lg_u32 s30, 1
	s_cbranch_scc1 .LBB0_124
	s_barrier
